# gdn_prep: DPP prefix scan for the cumulative decay; next-item prefetch issue compacted (three 32-bit row offsets, SGPR base, nine loads) instead of 350 instructions
# speedup vs baseline: 1.0113x; 1.0000x over previous
; DI void phase_gdn_prep(const Params& p, int l, char* smem) {
;     ...
;             const float sp = xx > 20.f ? xx : log1pf(expf(xx));
;             float g = -expf(p.a_log[l * 6 + h]) * sp;
; #pragma unroll
;             for (int off = 1; off < 64; off <<= 1) { const float v = __shfl_up(g, off); if (lane >= off) g += v; }
;             sgc[tid] = g; sbeta[tid] = 1.f / (1.f + expf(-bb));
;             if (tid == 63) p.glast[item] = expf(g);
.LBB0_279:
	s_or_b64 exec, exec, s[6:7]
	v_readlane_b32 s52, v251, 18
	v_readlane_b32 s60, v251, 26
	v_readlane_b32 s61, v251, 27
	s_add_u32 s4, s60, s4
	s_addc_u32 s5, s61, s5
	v_mov_b32_e32 v1, v109
	s_mov_b32 s2, 0x3fb8aa3b
	v_readlane_b32 s4, v249, 36
	v_readlane_b32 s5, v249, 37
	v_readlane_b32 s53, v251, 19
	v_readlane_b32 s54, v251, 20
	v_readlane_b32 s55, v251, 21
	v_readlane_b32 s56, v251, 22
	v_readlane_b32 s57, v251, 23
	v_readlane_b32 s58, v251, 24
	v_readlane_b32 s59, v251, 25
	v_readlane_b32 s62, v251, 28
	v_readlane_b32 s63, v251, 29
	v_readlane_b32 s64, v251, 30
	v_readlane_b32 s65, v251, 31
	v_readlane_b32 s66, v251, 32
	v_readlane_b32 s67, v251, 33
	s_waitcnt vmcnt(0)
	v_mul_f32_e32 v2, 0x3fb8aa3b, v1
	v_fma_f32 v3, v1, s2, -v2
	v_rndne_f32_e32 v4, v2
	v_fmac_f32_e32 v3, 0x32a5705f, v1
	v_sub_f32_e32 v2, v2, v4
	v_add_f32_e32 v2, v2, v3
	v_exp_f32_e32 v2, v2
	v_cvt_i32_f32_e32 v3, v4
	s_mov_b32 s2, 0xc2ce8ed0
	v_cmp_ngt_f32_e32 vcc, s2, v1
	s_mov_b32 s2, 0x42b17218
	v_ldexp_f32 v2, v2, v3
	v_cndmask_b32_e32 v2, 0, v2, vcc
	v_cmp_nlt_f32_e32 vcc, s2, v1
	s_nop 1
	v_cndmask_b32_e32 v1, v217, v2, vcc
	v_mul_f32_e64 v1, v0, -v1
	s_nop 1
	v_add_f32_dpp v1, v1, v1 row_shr:1 row_mask:0xf bank_mask:0xf
	s_nop 1
	v_add_f32_dpp v1, v1, v1 row_shr:2 row_mask:0xf bank_mask:0xf
	s_nop 1
	v_add_f32_dpp v1, v1, v1 row_shr:4 row_mask:0xf bank_mask:0xf
	s_nop 1
	v_add_f32_dpp v1, v1, v1 row_shr:8 row_mask:0xf bank_mask:0xf
	s_nop 1
	v_add_f32_dpp v1, v1, v1 row_bcast:15 row_mask:0xa bank_mask:0xf
	s_nop 1
	v_add_f32_dpp v1, v1, v1 row_bcast:31 row_mask:0xc bank_mask:0xf
	s_nop 0
	v_mov_b32_e32 v0, v1
	ds_write_b32 v63, v1
	v_mul_f32_e32 v1, 0xbfb8aa3b, v55
	v_rndne_f32_e32 v2, v1
	s_mov_b32 s4, 0xbfb8aa3b
	v_sub_f32_e32 v3, v1, v2
	v_fma_f32 v1, v55, s4, -v1
	v_fmac_f32_e32 v1, 0xb2a5705f, v55
	v_add_f32_e32 v1, v3, v1
	v_exp_f32_e32 v1, v1
	v_cvt_i32_f32_e32 v2, v2
	s_mov_b32 s4, 0x42ce8ed0
	v_cmp_nlt_f32_e32 vcc, s4, v55
	s_mov_b32 s4, 0xc2b17218
	v_ldexp_f32 v1, v1, v2
	v_cndmask_b32_e32 v1, 0, v1, vcc
	v_cmp_ngt_f32_e32 vcc, s4, v55
	s_nop 1
	v_cndmask_b32_e32 v1, v217, v1, vcc
	v_add_f32_e32 v1, 1.0, v1
	v_div_scale_f32 v2, s[4:5], v1, v1, 1.0
	v_rcp_f32_e32 v3, v2
	v_readlane_b32 s4, v249, 34
	v_readlane_b32 s5, v249, 35
	v_fma_f32 v4, -v2, v3, 1.0
	v_fmac_f32_e32 v3, v4, v3
	v_div_scale_f32 v4, vcc, 1.0, v1, 1.0
	v_mul_f32_e32 v5, v4, v3
	v_fma_f32 v6, -v2, v5, v4
	v_fmac_f32_e32 v5, v6, v3
	v_fma_f32 v2, -v2, v5, v4
	v_div_fmas_f32 v2, v2, v3, v5
	v_div_fixup_f32 v1, v2, v1, 1.0
	ds_write_b32 v64, v1
	s_and_b64 exec, exec, s[4:5]
	s_cbranch_execz .LBB0_281
	v_mul_f32_e32 v1, 0x3fb8aa3b, v0
	v_rndne_f32_e32 v2, v1
	s_mov_b32 s2, 0x3fb8aa3b
	v_sub_f32_e32 v3, v1, v2
	v_fma_f32 v1, v0, s2, -v1
	v_fmac_f32_e32 v1, 0x32a5705f, v0
	v_add_f32_e32 v1, v3, v1
	v_exp_f32_e32 v1, v1
	v_cvt_i32_f32_e32 v2, v2
	v_readlane_b32 s52, v250, 51
	s_mov_b32 s2, 0xc2ce8ed0
	s_lshl_b64 s[4:5], s[86:87], 2
	v_readlane_b32 s62, v250, 61
	v_ldexp_f32 v1, v1, v2
	v_cmp_ngt_f32_e32 vcc, s2, v0
	s_mov_b32 s2, 0x42b17218
	v_readlane_b32 s63, v250, 62
	s_add_u32 s4, s62, s4
	v_cndmask_b32_e32 v1, 0, v1, vcc
	v_cmp_nlt_f32_e32 vcc, s2, v0
	s_addc_u32 s5, s63, s5
	v_readlane_b32 s53, v250, 52
	v_cndmask_b32_e32 v0, v217, v1, vcc
	v_readlane_b32 s54, v250, 53
	v_readlane_b32 s55, v250, 54
	v_readlane_b32 s56, v250, 55
	v_readlane_b32 s57, v250, 56
	v_readlane_b32 s58, v250, 57
	v_readlane_b32 s59, v250, 58
	v_readlane_b32 s60, v250, 59
	v_readlane_b32 s61, v250, 60
	v_readlane_b32 s64, v250, 63
	v_readlane_b32 s65, v249, 0
	v_readlane_b32 s66, v249, 1
	v_readlane_b32 s67, v249, 2
	global_store_dword v189, v0, s[4:5]

; DI unsigned pk2(float lo, float hi) { f32x2 v = {lo, hi}; bf16x2_t r = __builtin_convertvector(v, bf16x2_t); return __builtin_bit_cast(unsigned, r); }
; DI int PINV(int s) { return (s & ~31) | ((s & 12) << 1) | ((s & 16) >> 2) | (s & 3); }
; DI void phase_gdn_prep(const Params& p, int l, char* smem) {
;     ...
;                 *(f32x4*)(sL + c * 64 + s0) = lv;
;                 u32x2 o2; o2[0] = pk2(qv[0], qv[1]); o2[1] = pk2(qv[2], qv[3]);
;                 *(u32x2*)(rec + 16384 + (c * 64 + PINV(s0)) * 2) = o2;
;             }
;         }
;         {
;             const int t = tid >> 2, part = tid & 3;
;             const float bt = sbeta[t], be = bt * __expf(sgc[t]);
; #pragma unroll
;             for (int j = 0; j < 16; ++j) { sv[t * 65 + part * 16 + j] *= bt; sk[t * 65 + part * 16 + j] *= be; }
;         }
;         __syncthreads();
;         { const int nxt = item + (int)gridDim.x; prefetch(nxt < 3072 ? nxt : item); }
.LBB0_313:
	v_mov_b32_e32 v6, v96
	v_mul_f32_e32 v0, v0, v185
	v_mul_f32_e32 v1, v1, v185
	v_mul_f32_e32 v2, v2, v185
	v_mul_f32_e32 v3, v3, v185
	v_mul_f32_e32 v0, v0, v12
	v_mul_f32_e32 v1, v1, v4
	v_mul_f32_e32 v2, v2, v5
	v_mul_f32_e32 v3, v3, v6
	v_cndmask_b32_e64 v0, 0, v0, s[16:17]
	v_cndmask_b32_e64 v1, 0, v1, s[20:21]
	v_cndmask_b32_e64 v2, 0, v2, s[24:25]
	v_mul_f32_e32 v5, v30, v5
	v_mul_f32_e32 v7, v28, v12
	v_mul_f32_e32 v4, v29, v4
	v_cndmask_b32_e64 v3, 0, v3, s[28:29]
	v_mul_f32_e32 v6, v31, v6
	ds_write_b128 v145, v[0:3] offset:50112
	v_cvt_pk_bf16_f32 v0, v7, v4
	v_cvt_pk_bf16_f32 v1, v5, v6
	global_store_dwordx2 v[20:21], v[0:1], off offset:72
	v_add_u32_e32 v1, 0x8200, v118
	ds_read_b32 v2, v74
	ds_read_b32 v0, v71
	ds_read2_b32 v[4:5], v1 offset0:0 offset1:1
	ds_read2_b32 v[6:7], v1 offset0:2 offset1:3
	ds_read2_b32 v[8:9], v1 offset0:4 offset1:5
	ds_read2_b32 v[10:11], v1 offset0:6 offset1:7
	ds_read2_b32 v[12:13], v1 offset0:8 offset1:9
	ds_read2_b32 v[14:15], v1 offset0:10 offset1:11
	ds_read2_b32 v[16:17], v1 offset0:12 offset1:13
	ds_read2_b32 v[18:19], v1 offset0:14 offset1:15
	v_readlane_b32 s4, v249, 16
	s_add_i32 s30, s86, s4
	s_cmpk_gt_i32 s30, 0xbff
	v_readlane_b32 s5, v249, 17
	s_cselect_b64 s[90:91], -1, 0
	s_cmpk_lt_i32 s30, 0xc00
	s_cselect_b32 s5, s30, s86
	s_ashr_i32 s6, s5, 8
	s_mul_hi_i32 s4, s6, 0x2aaaaaab
	s_lshr_b32 s7, s4, 31
	s_add_i32 s4, s4, s7
	s_mul_i32 s7, s4, 6
	s_lshl_b32 s5, s5, 6
	s_sub_i32 s86, s6, s7
	s_and_b32 s6, s5, 0x3fc0
	s_ashr_i32 s5, s4, 31
	s_sub_i32 s8, 2, s6
	s_lshl_b64 s[92:93], s[4:5], 14
	s_lshl_b32 s94, s86, 6
	v_cmp_lt_i32_e32 vcc, s8, v46
	s_or_b32 s92, s92, s6
	s_ashr_i32 s95, s94, 31
	s_and_b64 s[96:97], s[42:43], vcc
	s_waitcnt lgkmcnt(0)
	ds_read2_b32 v[20:21], v59 offset0:0 offset1:1
	ds_read2_b32 v[22:23], v59 offset0:2 offset1:3
	ds_read2_b32 v[24:25], v59 offset0:4 offset1:5
	ds_read2_b32 v[26:27], v59 offset0:6 offset1:7
	ds_read2_b32 v[28:29], v59 offset0:8 offset1:9
	ds_read2_b32 v[30:31], v59 offset0:10 offset1:11
	ds_read2_b32 v[32:33], v59 offset0:12 offset1:13
	ds_read2_b32 v[34:35], v59 offset0:14 offset1:15
	v_mul_f32_e32 v0, 0x3fb8aa3b, v0
	v_exp_f32_e32 v0, v0
	v_pk_mul_f32 v[4:5], v[2:3], v[4:5] op_sel_hi:[0,1]
	v_pk_mul_f32 v[6:7], v[2:3], v[6:7] op_sel_hi:[0,1]
	v_pk_mul_f32 v[8:9], v[2:3], v[8:9] op_sel_hi:[0,1]
	v_pk_mul_f32 v[10:11], v[2:3], v[10:11] op_sel_hi:[0,1]
	v_pk_mul_f32 v[12:13], v[2:3], v[12:13] op_sel_hi:[0,1]
	v_pk_mul_f32 v[14:15], v[2:3], v[14:15] op_sel_hi:[0,1]
	v_pk_mul_f32 v[16:17], v[2:3], v[16:17] op_sel_hi:[0,1]
	v_pk_mul_f32 v[18:19], v[2:3], v[18:19] op_sel_hi:[0,1]
	v_mul_f32_e32 v0, v2, v0
	s_waitcnt lgkmcnt(0)
	ds_write2_b32 v1, v4, v5 offset0:0 offset1:1
	ds_write2_b32 v1, v6, v7 offset0:2 offset1:3
	ds_write2_b32 v1, v8, v9 offset0:4 offset1:5
	ds_write2_b32 v1, v10, v11 offset0:6 offset1:7
	ds_write2_b32 v1, v12, v13 offset0:8 offset1:9
	ds_write2_b32 v1, v14, v15 offset0:10 offset1:11
	ds_write2_b32 v1, v16, v17 offset0:12 offset1:13
	ds_write2_b32 v1, v18, v19 offset0:14 offset1:15
	v_pk_mul_f32 v[20:21], v[0:1], v[20:21] op_sel_hi:[0,1]
	v_pk_mul_f32 v[22:23], v[0:1], v[22:23] op_sel_hi:[0,1]
	v_pk_mul_f32 v[24:25], v[0:1], v[24:25] op_sel_hi:[0,1]
	v_pk_mul_f32 v[26:27], v[0:1], v[26:27] op_sel_hi:[0,1]
	v_pk_mul_f32 v[28:29], v[0:1], v[28:29] op_sel_hi:[0,1]
	v_pk_mul_f32 v[30:31], v[0:1], v[30:31] op_sel_hi:[0,1]
	v_pk_mul_f32 v[32:33], v[0:1], v[32:33] op_sel_hi:[0,1]
	v_pk_mul_f32 v[34:35], v[0:1], v[34:35] op_sel_hi:[0,1]
	ds_write2_b32 v59, v20, v21 offset0:0 offset1:1
	ds_write2_b32 v59, v22, v23 offset0:2 offset1:3
	ds_write2_b32 v59, v24, v25 offset0:4 offset1:5
	ds_write2_b32 v59, v26, v27 offset0:6 offset1:7
	ds_write2_b32 v59, v28, v29 offset0:8 offset1:9
	ds_write2_b32 v59, v30, v31 offset0:10 offset1:11
	ds_write2_b32 v59, v32, v33 offset0:12 offset1:13
	ds_write2_b32 v59, v34, v35 offset0:14 offset1:15
	v_mov_b32_e32 v24, 0
	v_mov_b32_e32 v25, 0
	v_mov_b32_e32 v26, 0
	v_mov_b32_e32 v27, 0
	s_waitcnt lgkmcnt(0)
	s_barrier
; DI void phase_gdn_prep(const Params& p, int l, char* smem) {
;     ...
;     auto prefetch = [&](int it) {
;         const int chunk_ = it & 255, bh_ = it >> 8, h_ = bh_ % 6, b_ = bh_ / 6;
;         const int tb0_ = chunk_ * 64; const size_t row0_ = (size_t)b_ * T_ + tb0_;
; #pragma unroll
;         for (int part = 0; part < 3; ++part)
; #pragma unroll
;             for (int k = 0; k < 3; ++k) {
;                 const int c = tid + 256 * k, r = c >> 3, cc = c & 7;
;                 const bool ok = c < 67 * 8 && tb0_ + r - 3 >= 0;
;                 const bf16_t* src = p.proj + (row0_ + (ok ? r : 3) - 3) * DINP + part * 384 + h_ * 64 + cc * 8;
;                 const u32x4 v = *(const u32x4*)src;
;                 raw[part * 3 + k] = ok ? v : (u32x4){0u, 0u, 0u, 0u};
;             }
;         if (tid < 64) { pbb = p.side[(row0_ + tid) * 12 + h_]; paa = p.side[(row0_ + tid) * 12 + 6 + h_]; }
	v_cmp_lt_i32_e32 vcc, s8, v50
	s_and_b64 s[4:5], s[44:45], vcc
	v_cmp_lt_i32_e32 vcc, s8, v52
	s_and_b64 s[6:7], s[46:47], vcc
	v_readlane_b32 s56, v250, 55
	v_readlane_b32 s57, v250, 56
	s_lshl_b32 s2, s94, 1
	v_lshlrev_b32_e32 v188, 1, v48
	v_mov_b32_e32 v0, 0
	v_mov_b32_e32 v1, 0
	v_mov_b32_e32 v2, 0
	v_mov_b32_e32 v3, 0
	v_mov_b32_e32 v4, 0
	v_mov_b32_e32 v5, 0
	v_mov_b32_e32 v6, 0
	v_mov_b32_e32 v7, 0
	v_mov_b32_e32 v8, 0
	v_mov_b32_e32 v9, 0
	v_mov_b32_e32 v10, 0
	v_mov_b32_e32 v11, 0
	v_mov_b32_e32 v12, 0
	v_mov_b32_e32 v13, 0
	v_mov_b32_e32 v14, 0
	v_mov_b32_e32 v15, 0
	v_mov_b32_e32 v16, 0
	v_mov_b32_e32 v17, 0
	v_mov_b32_e32 v18, 0
	v_mov_b32_e32 v19, 0
	v_mov_b32_e32 v20, 0
	v_mov_b32_e32 v21, 0
	v_mov_b32_e32 v22, 0
	v_mov_b32_e32 v23, 0
	v_mov_b32_e32 v24, 0
	v_mov_b32_e32 v25, 0
	v_mov_b32_e32 v26, 0
	v_mov_b32_e32 v27, 0
	v_mov_b32_e32 v28, 0
	v_mov_b32_e32 v29, 0
	v_mov_b32_e32 v30, 0
	v_mov_b32_e32 v31, 0
	v_mov_b32_e32 v32, 0
	v_mov_b32_e32 v33, 0
	v_mov_b32_e32 v34, 0
	v_mov_b32_e32 v35, 0
	v_add_u32_e32 v108, s92, v46
	v_add_u32_e32 v108, -3, v108
	v_mul_u32_u24_e32 v108, 0x1800, v108
	v_add3_u32 v108, v108, s2, v188
	v_add_u32_e32 v109, s92, v50
	v_add_u32_e32 v109, -3, v109
	v_mul_u32_u24_e32 v109, 0x1800, v109
	v_add3_u32 v109, v109, s2, v188
	v_add_u32_e32 v110, s92, v52
	v_add_u32_e32 v110, -3, v110
	v_mul_u32_u24_e32 v110, 0x1800, v110
	v_add3_u32 v110, v110, s2, v188
	s_and_saveexec_b64 s[98:99], s[96:97]
	global_load_dwordx4 v[24:27], v108, s[56:57]
	global_load_dwordx4 v[12:15], v108, s[56:57] offset:768
	global_load_dwordx4 v[0:3], v108, s[56:57] offset:1536
	s_mov_b64 exec, s[98:99]
	s_and_saveexec_b64 s[98:99], s[4:5]
	global_load_dwordx4 v[28:31], v109, s[56:57]
	global_load_dwordx4 v[16:19], v109, s[56:57] offset:768
	global_load_dwordx4 v[4:7], v109, s[56:57] offset:1536
	s_mov_b64 exec, s[98:99]
	s_and_saveexec_b64 s[98:99], s[6:7]
	global_load_dwordx4 v[32:35], v110, s[56:57]
	global_load_dwordx4 v[20:23], v110, s[56:57] offset:768
	global_load_dwordx4 v[8:11], v110, s[56:57] offset:1536
	s_mov_b64 exec, s[98:99]
	v_readlane_b32 s52, v250, 51
	v_readlane_b32 s53, v250, 52
	v_readlane_b32 s54, v250, 53
	v_readlane_b32 s55, v250, 54
	v_readlane_b32 s58, v250, 57
	v_readlane_b32 s59, v250, 58
	v_readlane_b32 s60, v250, 59
	v_readlane_b32 s61, v250, 60
	v_readlane_b32 s62, v250, 61
	v_readlane_b32 s63, v250, 62
	v_readlane_b32 s64, v250, 63
	v_readlane_b32 s65, v249, 0
	v_readlane_b32 s66, v249, 1
	v_readlane_b32 s67, v249, 2
	s_and_saveexec_b64 s[4:5], s[38:39]
	s_cbranch_execz .LBB0_333
	v_readlane_b32 s52, v250, 51
	v_lshl_add_u64 v[36:37], s[92:93], 0, v[40:41]
	v_readlane_b32 s64, v250, 63
	v_readlane_b32 s65, v249, 0
	s_ashr_i32 s87, s86, 31
	v_readlane_b32 s53, v250, 52
	v_mad_u64_u32 v[38:39], s[6:7], v36, 48, s[64:65]
	v_mov_b32_e32 v36, v39
	v_mad_u64_u32 v[36:37], s[6:7], v37, 48, v[36:37]
	v_mov_b32_e32 v39, v36
	v_lshl_add_u64 v[36:37], s[86:87], 2, v[38:39]
	global_load_dword v55, v[36:37], off
	global_load_dword v49, v[36:37], off offset:24
	v_readlane_b32 s54, v250, 53
	v_readlane_b32 s55, v250, 54
	v_readlane_b32 s56, v250, 55
	v_readlane_b32 s57, v250, 56
	v_readlane_b32 s58, v250, 57
	v_readlane_b32 s59, v250, 58
	v_readlane_b32 s60, v250, 59
	v_readlane_b32 s61, v250, 60
	v_readlane_b32 s62, v250, 61
	v_readlane_b32 s63, v250, 62
	v_readlane_b32 s66, v249, 1
	v_readlane_b32 s67, v249, 2
